# prompt attention: step-closing barrier placed directly after the last PV MFMA (right behind the staging writes); row-max chain, rescale check and softmax block all after it
# baseline (speedup 1.0000x reference)
; __device__ __forceinline__ void partialSM(f32x16& p0, f32x16& p1, float& m_reg, float& mn, float& alpha) {
;     ...
;     if (__builtin_expect(__all((pmax - m_reg) * SCALE <= THR), 1)) { mn = m_reg; alpha = 1.f; }
;     else { mn = fmaxf(m_reg, pmax); alpha = __builtin_amdgcn_exp2f((m_reg - mn) * C2); m_reg = mn; }
;     const float mnL = -mn * C2;
;     for (int r = 0; r < 16; ++r) p0[r] = fmaf(p0[r], C2, mnL); for (int r = 0; r < 16; ++r) p1[r] = fmaf(p1[r], C2, mnL);
;     for (int r = 0; r < 16; ++r) p0[r] = __builtin_amdgcn_exp2f(p0[r]);
; }
; __device__ __forceinline__ void finishSM(f32x16& p0, f32x16& p1, float alpha, float& l_reg, bf16x8& pa0, bf16x8& pa1, bf16x8& pa2, bf16x8& pa3) {
;     for (int r = 0; r < 16; ++r) p1[r] = __builtin_amdgcn_exp2f(p1[r]);
;     float ps = 0; for (int r = 0; r < 16; ++r) ps += p0[r]; for (int r = 0; r < 16; ++r) ps += p1[r];
;     { auto rr = __builtin_amdgcn_permlane32_swap(__float_as_uint(ps), __float_as_uint(ps), false, false);
;       ps = __uint_as_float(rr[0]) + __uint_as_float(rr[1]); }
;     l_reg = l_reg * alpha + ps;
;     ...
;     PK4(p0, 0, pa0); PK4(p0, 8, pa1); PK4(p1, 0, pa2); PK4(p1, 8, pa3);
;     ...
; }
; template <int KB, bool SK>
; __device__ __forceinline__ void qkt(f32x16& p0, f32x16& p1, const char* K_lds, const float* B_lds, int r32, int hi, const bf16x8* qr, bool act) {
;     if (SK && !act) { const float NEG = -__builtin_inff();
; #pragma unroll
;         for (int r = 0; r < 16; ++r) { p0[r] = NEG; p1[r] = NEG; } return; }
;     ...
;     p0 = f32x16{}; p1 = f32x16{};
;     ...
;     p0 = *(const f32x16*)(B_lds + KB * 64 + hi * 32); p1 = *(const f32x16*)(B_lds + KB * 64 + hi * 32 + 16);
;     ...
;     const char* kb[4];
; #pragma unroll
;     for (int dd = 0; dd < 4; ++dd) kb[dd] = K_lds + KB * SHM_K + KSWZ(r32, (dd * 16 + hi * 8) * 2);
; #pragma unroll
;     for (int d0 = 0; d0 < 8; ++d0) { const char* a = kb[d0 & 3] + (d0 >> 2) * 128;
;         bf16x8 b0 = *reinterpret_cast<const bf16x8*>(a);
;         bf16x8 b1 = *reinterpret_cast<const bf16x8*>(a + 32 * 256);
;         p0 = __builtin_amdgcn_mfma_f32_32x32x16_bf16(b0, qr[d0], p0, 0, 0, 0);
;         p1 = __builtin_amdgcn_mfma_f32_32x32x16_bf16(b1, qr[d0], p1, 0, 0, 0); }
.LBB0_1246:
	v_cndmask_b32_e64 v180, v2, v247, s[4:5]
	v_mul_f32_e32 v2, 0xbe0293ee, v180
	s_waitcnt vmcnt(1)
	v_fmamk_f32 v13, v138, 0x3e0293ee, v2
	v_fmamk_f32 v138, v139, 0x3e0293ee, v2
	v_fmamk_f32 v139, v140, 0x3e0293ee, v2
	v_fmamk_f32 v140, v141, 0x3e0293ee, v2
	v_fmamk_f32 v141, v142, 0x3e0293ee, v2
	v_mov_b32_e32 v142, v2
	v_fmamk_f32 v3, v128, 0x3e0293ee, v2
	v_fmamk_f32 v4, v129, 0x3e0293ee, v2
	v_fmamk_f32 v5, v130, 0x3e0293ee, v2
	v_fmamk_f32 v6, v131, 0x3e0293ee, v2
	v_fmamk_f32 v7, v132, 0x3e0293ee, v2
	v_fmamk_f32 v8, v133, 0x3e0293ee, v2
	v_fmamk_f32 v9, v134, 0x3e0293ee, v2
	v_fmamk_f32 v10, v135, 0x3e0293ee, v2
	v_fmamk_f32 v11, v136, 0x3e0293ee, v2
	v_fmamk_f32 v12, v137, 0x3e0293ee, v2
	v_fmac_f32_e32 v142, 0x3e0293ee, v143
	v_exp_f32_e32 v191, v3
	v_exp_f32_e32 v193, v4
	v_exp_f32_e32 v189, v5
	v_exp_f32_e32 v192, v6
	v_exp_f32_e32 v188, v7
	v_exp_f32_e32 v190, v8
	v_exp_f32_e32 v186, v9
	v_exp_f32_e32 v187, v10
	v_exp_f32_e32 v182, v11
	v_exp_f32_e32 v185, v12
	s_waitcnt vmcnt(0)
	v_exp_f32_e32 v179, v13
	v_exp_f32_e32 v183, v138
	v_exp_f32_e32 v177, v139
	v_exp_f32_e32 v184, v140
	v_exp_f32_e32 v178, v141
	v_exp_f32_e32 v181, v142
	v_pk_fma_f32 v[128:129], v[126:127], s[44:45], v[2:3] op_sel_hi:[1,0,0]
	v_pk_fma_f32 v[130:131], v[124:125], s[44:45], v[2:3] op_sel_hi:[1,0,0]
	v_pk_fma_f32 v[132:133], v[122:123], s[44:45], v[2:3] op_sel_hi:[1,0,0]
	v_pk_fma_f32 v[134:135], v[120:121], s[44:45], v[2:3] op_sel_hi:[1,0,0]
	v_pk_fma_f32 v[136:137], v[118:119], s[44:45], v[2:3] op_sel_hi:[1,0,0]
	v_pk_fma_f32 v[138:139], v[116:117], s[44:45], v[2:3] op_sel_hi:[1,0,0]
	v_pk_fma_f32 v[140:141], v[114:115], s[44:45], v[2:3] op_sel_hi:[1,0,0]
	v_pk_fma_f32 v[142:143], v[112:113], s[44:45], v[2:3] op_sel_hi:[1,0,0]
	v_add_f32_e32 v2, v244, v245
	v_fmac_f32_e32 v2, v240, v241
	v_add_f32_e32 v241, v249, v250
	s_addk_i32 s68, 0x80
	s_add_i32 s61, s61, 2
	v_fmac_f32_e32 v241, v2, v15
	v_add_u32_e32 v243, 0xffffff80, v243
	s_cmp_ge_i32 s61, s59
	v_add_u32_e32 v14, 0x40000, v14
	v_mov_b32_e32 v240, v0
	s_cbranch_scc1 .LBB0_1263
.LBB0_1247:
	v_add_u32_e32 v200, v230, v219
	v_add_u32_e32 v248, s68, v200
	v_add_u32_e32 v200, 1, v248
	v_lshl_add_u64 v[2:3], v[200:201], 2, s[66:67]
	v_mov_b32_e32 v15, v1
	v_add_u32_e32 v200, 0x10000, v14
	v_lshlrev_b64 v[10:11], 1, v[14:15]
	v_lshlrev_b64 v[12:13], 1, v[200:201]
	global_load_dword v246, v[2:3], off
	v_lshl_add_u64 v[2:3], s[64:65], 0, v[10:11]
	v_lshl_add_u64 v[6:7], s[64:65], 0, v[12:13]
	v_lshl_add_u64 v[10:11], s[62:63], 0, v[10:11]
	global_load_dwordx4 v[2:5], v[2:3], off
	s_nop 0
	global_load_dwordx4 v[6:9], v[6:7], off
	v_lshl_add_u64 v[210:211], s[62:63], 0, v[12:13]
	global_load_dwordx4 v[10:13], v[10:11], off
	s_nop 0
	global_load_dwordx4 v[210:213], v[210:211], off
	v_add_u32_e32 v0, 0x10900, v236
	ds_read_b128 v[100:103], v0
	ds_read_b128 v[104:107], v0 offset:16
	ds_read_b128 v[108:111], v0 offset:32
	s_waitcnt vmcnt(7)
	ds_read_b128 v[112:115], v0 offset:48
	ds_read_b128 v[96:99], v0 offset:112
	ds_read_b128 v[92:95], v0 offset:96
	ds_read_b128 v[88:91], v0 offset:80
	ds_read_b128 v[84:87], v0 offset:64
	ds_read_b128 v[202:205], v235 offset:49152
	ds_read_b128 v[206:209], v235 offset:57344
	v_add_f32_e32 v80, 0, v191
	v_add_f32_e32 v80, v193, v80
	v_add_f32_e32 v80, v189, v80
	s_waitcnt lgkmcnt(1)
	v_mfma_f32_32x32x16_bf16 v[100:115], v[202:205], v[172:175], v[100:115]
	v_add_f32_e32 v80, v192, v80
	v_add_f32_e32 v80, v188, v80
	v_add_f32_e32 v80, v190, v80
	v_add_f32_e32 v80, v186, v80
	v_add_f32_e32 v80, v187, v80
	v_add_f32_e32 v80, v182, v80
	v_add_f32_e32 v80, v185, v80
	s_waitcnt lgkmcnt(0)
	v_mfma_f32_32x32x16_bf16 v[84:99], v[206:209], v[172:175], v[84:99]
	ds_read_b128 v[202:205], v234 offset:49152
	ds_read_b128 v[206:209], v234 offset:57344
	v_add_f32_e32 v80, v179, v80
	v_add_f32_e32 v80, v183, v80
	v_exp_f32_e32 v0, v142
	v_add_f32_e32 v80, v177, v80
	v_add_f32_e32 v80, v184, v80
	v_add_f32_e32 v80, v178, v80
	s_waitcnt lgkmcnt(1)
	v_mfma_f32_32x32x16_bf16 v[100:115], v[202:205], v[168:171], v[100:115]
	v_add_f32_e32 v80, v181, v80
	v_add_f32_e32 v80, v0, v80
	v_exp_f32_e32 v194, v135
	v_exp_f32_e32 v195, v132
	v_exp_f32_e32 v196, v133
	v_exp_f32_e32 v197, v130
	v_exp_f32_e32 v198, v131
	s_waitcnt lgkmcnt(0)
	v_mfma_f32_32x32x16_bf16 v[84:99], v[206:209], v[168:171], v[84:99]
	ds_read_b128 v[202:205], v233 offset:49152
	ds_read_b128 v[206:209], v233 offset:57344
	v_exp_f32_e32 v127, v128
	v_exp_f32_e32 v128, v129
	s_sub_i32 s4, s68, 63
	s_waitcnt lgkmcnt(1)
	v_mfma_f32_32x32x16_bf16 v[100:115], v[202:205], v[164:167], v[100:115]
	s_waitcnt lgkmcnt(0)
	v_mfma_f32_32x32x16_bf16 v[84:99], v[206:209], v[164:167], v[84:99]
	ds_read_b128 v[202:205], v232 offset:49152
	ds_read_b128 v[206:209], v232 offset:57344
	s_waitcnt lgkmcnt(1)
	v_mfma_f32_32x32x16_bf16 v[100:115], v[202:205], v[160:163], v[100:115]
	s_waitcnt lgkmcnt(0)
	v_mfma_f32_32x32x16_bf16 v[84:99], v[206:209], v[160:163], v[84:99]
	ds_read_b128 v[202:205], v235 offset:49280
	ds_read_b128 v[206:209], v235 offset:57472
	s_waitcnt lgkmcnt(1)
	v_mfma_f32_32x32x16_bf16 v[100:115], v[202:205], v[156:159], v[100:115]
	s_waitcnt lgkmcnt(0)
	v_mfma_f32_32x32x16_bf16 v[84:99], v[206:209], v[156:159], v[84:99]
	ds_read_b128 v[202:205], v234 offset:49280
	ds_read_b128 v[206:209], v234 offset:57472
	s_waitcnt lgkmcnt(1)
	v_mfma_f32_32x32x16_bf16 v[100:115], v[202:205], v[152:155], v[100:115]
	s_waitcnt lgkmcnt(0)
	v_mfma_f32_32x32x16_bf16 v[84:99], v[206:209], v[152:155], v[84:99]
	ds_read_b128 v[202:205], v233 offset:49280
	ds_read_b128 v[206:209], v233 offset:57472
	s_waitcnt lgkmcnt(1)
; __device__ __forceinline__ void finishSM(f32x16& p0, f32x16& p1, float alpha, float& l_reg, bf16x8& pa0, bf16x8& pa1, bf16x8& pa2, bf16x8& pa3) {
;     for (int r = 0; r < 16; ++r) p1[r] = __builtin_amdgcn_exp2f(p1[r]);
;     float ps = 0; for (int r = 0; r < 16; ++r) ps += p0[r]; for (int r = 0; r < 16; ++r) ps += p1[r];
;     { auto rr = __builtin_amdgcn_permlane32_swap(__float_as_uint(ps), __float_as_uint(ps), false, false);
;       ps = __uint_as_float(rr[0]) + __uint_as_float(rr[1]); }
;     l_reg = l_reg * alpha + ps;
;     ...
;     PK4(p0, 0, pa0); PK4(p0, 8, pa1); PK4(p1, 0, pa2); PK4(p1, 8, pa3);
; template <int VB, bool SK>
; __device__ __forceinline__ void pv_tile(f32x16* o, int vb0, bf16x8 pa0, bf16x8 pa1, bf16x8 pa2, bf16x8 pa3, bool act) {
;     ...
;     PV_D0(0); PV_D0(1); PV_D0(2); PV_D0(3);
	v_mfma_f32_32x32x16_bf16 v[100:115], v[202:205], v[148:151], v[100:115]
	s_waitcnt lgkmcnt(0)
	v_mfma_f32_32x32x16_bf16 v[84:99], v[206:209], v[148:151], v[84:99]
	ds_read_b128 v[202:205], v232 offset:49280
	ds_read_b128 v[206:209], v232 offset:57472
	s_waitcnt lgkmcnt(1)
	v_mfma_f32_32x32x16_bf16 v[100:115], v[202:205], v[144:147], v[100:115]
	v_exp_f32_e32 v202, v143
	v_exp_f32_e32 v203, v140
	v_exp_f32_e32 v204, v141
	v_exp_f32_e32 v205, v138
	v_add_f32_e32 v80, v202, v80
	v_add_f32_e32 v80, v203, v80
	v_add_f32_e32 v80, v204, v80
	s_waitcnt lgkmcnt(0)
	v_mfma_f32_32x32x16_bf16 v[84:99], v[206:209], v[144:147], v[84:99]
	v_exp_f32_e32 v206, v139
	v_exp_f32_e32 v207, v136
	v_exp_f32_e32 v208, v137
	v_exp_f32_e32 v209, v134
	v_add_f32_e32 v80, v205, v80
	v_add_f32_e32 v80, v206, v80
	v_add_f32_e32 v80, v207, v80
	v_add_f32_e32 v80, v208, v80
	v_add_f32_e32 v80, v209, v80
	v_add_f32_e32 v80, v194, v80
	v_add_f32_e32 v80, v195, v80
	v_add_f32_e32 v80, v196, v80
	v_add_f32_e32 v80, v197, v80
	v_add_f32_e32 v80, v198, v80
	v_add_f32_e32 v80, v127, v80
	v_add_f32_e32 v244, v128, v80
	v_mov_b32_e32 v245, v244
	s_nop 1
	v_permlane32_swap_b32_e32 v244, v245
	v_cvt_pk_bf16_f32 v80, v191, v193
	v_cvt_pk_bf16_f32 v81, v189, v192
	v_cvt_pk_bf16_f32 v82, v188, v190
	v_cvt_pk_bf16_f32 v83, v186, v187
	s_waitcnt vmcnt(6)
	v_cvt_pk_bf16_f32 v116, v182, v185
	v_cvt_pk_bf16_f32 v117, v179, v183
	v_cvt_pk_bf16_f32 v118, v177, v184
	v_cvt_pk_bf16_f32 v119, v178, v181
	s_waitcnt vmcnt(5)
	v_cvt_pk_bf16_f32 v120, v0, v202
	v_cvt_pk_bf16_f32 v121, v203, v204
	v_cvt_pk_bf16_f32 v122, v205, v206
	v_cvt_pk_bf16_f32 v123, v207, v208
	v_cvt_pk_bf16_f32 v124, v209, v194
	v_cvt_pk_bf16_f32 v125, v195, v196
	v_cvt_pk_bf16_f32 v126, v197, v198
	v_cvt_pk_bf16_f32 v127, v127, v128
	v_permlane32_swap_b32_e32 v80, v82
	v_permlane32_swap_b32_e32 v81, v83
	v_permlane32_swap_b32_e32 v116, v118
	v_permlane32_swap_b32_e32 v117, v119
	v_permlane32_swap_b32_e32 v120, v122
	v_permlane32_swap_b32_e32 v121, v123
	v_permlane32_swap_b32_e32 v124, v126
	v_permlane32_swap_b32_e32 v125, v127
	ds_read_b64_tr_b16 v[128:129], v227 offset:0
	ds_read_b64_tr_b16 v[130:131], v227 offset:0x800
	ds_read_b64_tr_b16 v[132:133], v227 offset:0x1000
	ds_read_b64_tr_b16 v[134:135], v227 offset:0x1800
	ds_read_b64_tr_b16 v[136:137], v227 offset:0x2000
	ds_read_b64_tr_b16 v[138:139], v227 offset:0x2800
	ds_read_b64_tr_b16 v[140:141], v227 offset:0x3000
	ds_read_b64_tr_b16 v[142:143], v227 offset:0x3800
	s_waitcnt lgkmcnt(0)
	s_nop 0
	v_mfma_f32_32x32x16_bf16 v[64:79], v[80:83], v[128:131], v[64:79]
	ds_read_b64_tr_b16 v[128:129], v227 offset:0x200
	ds_read_b64_tr_b16 v[130:131], v227 offset:0xa00
	v_mfma_f32_32x32x16_bf16 v[64:79], v[116:119], v[132:135], v[64:79]
	ds_read_b64_tr_b16 v[132:133], v227 offset:0x1200
	ds_read_b64_tr_b16 v[134:135], v227 offset:0x1a00
	v_mfma_f32_32x32x16_bf16 v[64:79], v[120:123], v[136:139], v[64:79]
	ds_read_b64_tr_b16 v[136:137], v227 offset:0x2200
	ds_read_b64_tr_b16 v[138:139], v227 offset:0x2a00
	v_mfma_f32_32x32x16_bf16 v[64:79], v[124:127], v[140:143], v[64:79]
	ds_read_b64_tr_b16 v[140:141], v227 offset:0x3200
	ds_read_b64_tr_b16 v[142:143], v227 offset:0x3a00
	s_waitcnt lgkmcnt(0)
	v_mfma_f32_32x32x16_bf16 v[48:63], v[80:83], v[128:131], v[48:63]
	ds_read_b64_tr_b16 v[128:129], v227 offset:0x400
	ds_read_b64_tr_b16 v[130:131], v227 offset:0xc00
	v_mfma_f32_32x32x16_bf16 v[48:63], v[116:119], v[132:135], v[48:63]
	ds_read_b64_tr_b16 v[132:133], v227 offset:0x1400
	ds_read_b64_tr_b16 v[134:135], v227 offset:0x1c00
	v_mfma_f32_32x32x16_bf16 v[48:63], v[120:123], v[136:139], v[48:63]
	ds_read_b64_tr_b16 v[136:137], v227 offset:0x2400
	ds_read_b64_tr_b16 v[138:139], v227 offset:0x2c00
	v_mfma_f32_32x32x16_bf16 v[48:63], v[124:127], v[140:143], v[48:63]
	ds_read_b64_tr_b16 v[140:141], v227 offset:0x3400
	ds_read_b64_tr_b16 v[142:143], v227 offset:0x3c00
	s_waitcnt lgkmcnt(0)
	v_mfma_f32_32x32x16_bf16 v[32:47], v[80:83], v[128:131], v[32:47]
	ds_read_b64_tr_b16 v[128:129], v227 offset:0x600
	ds_read_b64_tr_b16 v[130:131], v227 offset:0xe00
	v_mfma_f32_32x32x16_bf16 v[32:47], v[116:119], v[132:135], v[32:47]
	ds_read_b64_tr_b16 v[132:133], v227 offset:0x1600
	ds_read_b64_tr_b16 v[134:135], v227 offset:0x1e00
	v_mfma_f32_32x32x16_bf16 v[32:47], v[120:123], v[136:139], v[32:47]
	ds_read_b64_tr_b16 v[136:137], v227 offset:0x2600
	ds_read_b64_tr_b16 v[138:139], v227 offset:0x2e00
	v_mfma_f32_32x32x16_bf16 v[32:47], v[124:127], v[140:143], v[32:47]
	ds_read_b64_tr_b16 v[140:141], v227 offset:0x3600
	ds_read_b64_tr_b16 v[142:143], v227 offset:0x3e00
	s_waitcnt lgkmcnt(0)
	s_barrier
; __device__ __forceinline__ void mask_tile(f32x16& p0, f32x16& p1, int dq, unsigned W) {
;     const float NEG = -__builtin_inff();
; #pragma unroll
;     for (int r = 0; r < 16; ++r) {
;         const int c = (r & 3) + 8 * (r >> 2);
;         if ((unsigned)(dq - c) >= W) p0[r] = NEG;
;         if ((unsigned)(dq - c - 32) >= W) p1[r] = NEG;
;     }
; }
	s_waitcnt vmcnt(0)
	ds_write_b128 v237, v[2:5]
	ds_write_b128 v238, v[6:9]
	ds_write_b32 v242, v246
	ds_write_b128 v222, v[10:13] offset:32768
	ds_write_b128 v222, v[210:213] offset:40960
	v_mfma_f32_32x32x16_bf16 v[16:31], v[80:83], v[128:131], v[16:31]
	s_cmp_le_i32 s68, s57
	s_cselect_b64 s[28:29], -1, 0
	s_cmp_gt_i32 s4, s58
	s_cselect_b64 s[4:5], -1, 0
	s_and_b64 s[4:5], s[28:29], s[4:5]
	s_and_b64 vcc, exec, s[4:5]
	v_mfma_f32_32x32x16_bf16 v[16:31], v[116:119], v[132:135], v[16:31]
	v_mfma_f32_32x32x16_bf16 v[16:31], v[120:123], v[136:139], v[16:31]
	v_mfma_f32_32x32x16_bf16 v[16:31], v[124:127], v[140:143], v[16:31]
	s_waitcnt lgkmcnt(0)
	s_barrier
	s_cbranch_vccnz .LBB0_1249
	v_add_u32_e32 v0, 0x107b, v243
	v_cmp_gt_u32_e32 vcc, s81, v0
	v_add_u32_e32 v0, 0x5b, v243
	s_nop 0
	v_cndmask_b32_e32 v100, v216, v100, vcc
	v_cmp_lt_u32_e32 vcc, s82, v0
	v_add_u32_e32 v0, 0x7a, v243
	s_nop 0
	v_cndmask_b32_e32 v84, v216, v84, vcc
	v_cmp_lt_u32_e32 vcc, s82, v0
	v_add_u32_e32 v0, 0x5a, v243
	s_nop 0
	v_cndmask_b32_e32 v101, v216, v101, vcc
	v_cmp_lt_u32_e32 vcc, s82, v0
	v_add_u32_e32 v0, 0x79, v243
	s_nop 0
	v_cndmask_b32_e32 v85, v216, v85, vcc
	v_cmp_lt_u32_e32 vcc, s82, v0
	v_add_u32_e32 v0, 0x59, v243
	s_nop 0
	v_cndmask_b32_e32 v102, v216, v102, vcc
	v_cmp_lt_u32_e32 vcc, s82, v0
	v_add_u32_e32 v0, 0x78, v243
	s_nop 0
	v_cndmask_b32_e32 v86, v216, v86, vcc
	v_cmp_lt_u32_e32 vcc, s82, v0
	v_add_u32_e32 v0, 0x58, v243
	s_nop 0
	v_cndmask_b32_e32 v103, v216, v103, vcc
	v_cmp_lt_u32_e32 vcc, s82, v0
	v_add_u32_e32 v0, 0x73, v243
	s_nop 0
	v_cndmask_b32_e32 v87, v216, v87, vcc
	v_cmp_lt_u32_e32 vcc, s82, v0
	v_add_u32_e32 v0, 0x53, v243
	s_nop 0
	v_cndmask_b32_e32 v104, v216, v104, vcc
	v_cmp_lt_u32_e32 vcc, s82, v0
	v_add_u32_e32 v0, 0x72, v243
	s_nop 0
	v_cndmask_b32_e32 v88, v216, v88, vcc
	v_cmp_lt_u32_e32 vcc, s82, v0
	v_add_u32_e32 v0, 0x52, v243
	s_nop 0
	v_cndmask_b32_e32 v105, v216, v105, vcc
	v_cmp_lt_u32_e32 vcc, s82, v0
	v_add_u32_e32 v0, 0x71, v243
	s_nop 0
	v_cndmask_b32_e32 v89, v216, v89, vcc
	v_cmp_lt_u32_e32 vcc, s82, v0
	v_add_u32_e32 v0, 0x51, v243
	s_nop 0
	v_cndmask_b32_e32 v106, v216, v106, vcc
	v_cmp_lt_u32_e32 vcc, s82, v0
	v_add_u32_e32 v0, 0x70, v243
	s_nop 0
	v_cndmask_b32_e32 v90, v216, v90, vcc
	v_cmp_lt_u32_e32 vcc, s82, v0
	v_add_u32_e32 v0, 0x50, v243
	s_nop 0
	v_cndmask_b32_e32 v107, v216, v107, vcc
	v_cmp_lt_u32_e32 vcc, s82, v0
	v_add_u32_e32 v0, 0x6b, v243
	s_nop 0
	v_cndmask_b32_e32 v91, v216, v91, vcc
	v_cmp_lt_u32_e32 vcc, s82, v0
	v_add_u32_e32 v0, 0x4b, v243
	s_nop 0
	v_cndmask_b32_e32 v108, v216, v108, vcc
	v_cmp_lt_u32_e32 vcc, s82, v0
	v_add_u32_e32 v0, 0x6a, v243
	s_nop 0
	v_cndmask_b32_e32 v92, v216, v92, vcc
	v_cmp_lt_u32_e32 vcc, s82, v0
	v_add_u32_e32 v0, 0x4a, v243
	s_nop 0
	v_cndmask_b32_e32 v109, v216, v109, vcc
	v_cmp_lt_u32_e32 vcc, s82, v0
	v_add_u32_e32 v0, 0x69, v243
	s_nop 0
	v_cndmask_b32_e32 v93, v216, v93, vcc
	v_cmp_lt_u32_e32 vcc, s82, v0
	v_add_u32_e32 v0, 0x49, v243
	s_nop 0
	v_cndmask_b32_e32 v110, v216, v110, vcc
	v_cmp_lt_u32_e32 vcc, s82, v0
	v_add_u32_e32 v0, 0x68, v243
	s_nop 0
	v_cndmask_b32_e32 v94, v216, v94, vcc
	v_cmp_lt_u32_e32 vcc, s82, v0
	v_add_u32_e32 v0, 0x48, v243
	s_nop 0
	v_cndmask_b32_e32 v111, v216, v111, vcc
	v_cmp_lt_u32_e32 vcc, s82, v0
	v_add_u32_e32 v0, 0x63, v243
	s_nop 0
	v_cndmask_b32_e32 v95, v216, v95, vcc
	v_cmp_lt_u32_e32 vcc, s82, v0
	v_add_u32_e32 v0, 0x43, v243
	s_nop 0
	v_cndmask_b32_e32 v112, v216, v112, vcc
	v_cmp_lt_u32_e32 vcc, s82, v0
	v_add_u32_e32 v0, 0x62, v243
	s_nop 0
	v_cndmask_b32_e32 v96, v216, v96, vcc
	v_cmp_lt_u32_e32 vcc, s82, v0
	v_add_u32_e32 v0, 0x42, v243
	s_nop 0
	v_cndmask_b32_e32 v113, v216, v113, vcc
	v_cmp_lt_u32_e32 vcc, s82, v0
	v_add_u32_e32 v0, 0x61, v243
	s_nop 0
	v_cndmask_b32_e32 v97, v216, v97, vcc
	v_cmp_lt_u32_e32 vcc, s82, v0
	v_add_u32_e32 v0, 0x41, v243
	s_nop 0
	v_cndmask_b32_e32 v114, v216, v114, vcc
	v_cmp_lt_u32_e32 vcc, s82, v0
	v_add_u32_e32 v0, 0x60, v243
	s_nop 0
	v_cndmask_b32_e32 v98, v216, v98, vcc
	v_cmp_lt_u32_e32 vcc, s82, v0
	v_add_u32_e32 v0, 64, v243
	s_nop 0
	v_cndmask_b32_e32 v115, v216, v115, vcc
	v_cmp_lt_u32_e32 vcc, s82, v0
	s_nop 1
	v_cndmask_b32_e32 v99, v216, v99, vcc

; __device__ __forceinline__ void partialSM(f32x16& p0, f32x16& p1, float& m_reg, float& mn, float& alpha) {
;     ...
;     if (__builtin_expect(__all((pmax - m_reg) * SCALE <= THR), 1)) { mn = m_reg; alpha = 1.f; }
;     else { mn = fmaxf(m_reg, pmax); alpha = __builtin_amdgcn_exp2f((m_reg - mn) * C2); m_reg = mn; }
;     const float mnL = -mn * C2;
;     for (int r = 0; r < 16; ++r) p0[r] = fmaf(p0[r], C2, mnL); for (int r = 0; r < 16; ++r) p1[r] = fmaf(p1[r], C2, mnL);
;     for (int r = 0; r < 16; ++r) p0[r] = __builtin_amdgcn_exp2f(p0[r]);
.LBB0_1253:
	v_cndmask_b32_e64 v247, v0, v180, s[4:5]
	v_mul_f32_e32 v0, 0xbe0293ee, v247
	v_fmamk_f32 v80, v100, 0x3e0293ee, v0
	v_fmamk_f32 v81, v101, 0x3e0293ee, v0
	v_fmamk_f32 v82, v102, 0x3e0293ee, v0
	v_fmamk_f32 v83, v103, 0x3e0293ee, v0
	v_fmamk_f32 v116, v104, 0x3e0293ee, v0
	v_fmamk_f32 v117, v105, 0x3e0293ee, v0
	v_fmamk_f32 v118, v106, 0x3e0293ee, v0
	v_fmamk_f32 v119, v107, 0x3e0293ee, v0
	v_fmamk_f32 v120, v108, 0x3e0293ee, v0
	v_fmamk_f32 v121, v109, 0x3e0293ee, v0
	v_fmamk_f32 v122, v110, 0x3e0293ee, v0
	v_fmamk_f32 v123, v111, 0x3e0293ee, v0
	v_fmamk_f32 v112, v112, 0x3e0293ee, v0
	v_fmamk_f32 v113, v113, 0x3e0293ee, v0
	v_fmamk_f32 v114, v114, 0x3e0293ee, v0
	v_fmamk_f32 v115, v115, 0x3e0293ee, v0
	v_fmamk_f32 v100, v84, 0x3e0293ee, v0
	v_fmamk_f32 v109, v85, 0x3e0293ee, v0
	v_fmamk_f32 v110, v86, 0x3e0293ee, v0
	v_fmamk_f32 v111, v87, 0x3e0293ee, v0
	v_fmamk_f32 v180, v88, 0x3e0293ee, v0
	v_fmamk_f32 v101, v89, 0x3e0293ee, v0
	v_fmamk_f32 v102, v90, 0x3e0293ee, v0
	v_fmamk_f32 v103, v91, 0x3e0293ee, v0
	v_fmamk_f32 v104, v92, 0x3e0293ee, v0
	v_fmamk_f32 v105, v93, 0x3e0293ee, v0
	v_fmamk_f32 v106, v94, 0x3e0293ee, v0
	v_fmamk_f32 v107, v95, 0x3e0293ee, v0
	v_exp_f32_e32 v80, v80
	v_exp_f32_e32 v81, v81
	v_exp_f32_e32 v82, v82
	v_exp_f32_e32 v83, v83
	v_exp_f32_e32 v84, v116
	v_exp_f32_e32 v85, v117
	v_exp_f32_e32 v86, v118
	v_exp_f32_e32 v87, v119
	v_exp_f32_e32 v88, v120
	v_exp_f32_e32 v89, v121
	v_exp_f32_e32 v90, v122
	v_exp_f32_e32 v91, v123
	v_exp_f32_e32 v92, v112
	v_exp_f32_e32 v93, v113
	v_exp_f32_e32 v94, v114
	v_exp_f32_e32 v95, v115
	v_fmamk_f32 v108, v96, 0x3e0293ee, v0
	v_fmamk_f32 v181, v97, 0x3e0293ee, v0
	v_fmamk_f32 v182, v98, 0x3e0293ee, v0
	v_fmac_f32_e32 v0, 0x3e0293ee, v99
	s_add_i32 s4, s61, 1
	s_cmp_lt_i32 s4, s59
	s_cselect_b64 s[28:29], -1, 0
	s_cmp_ge_i32 s4, s59
	s_cbranch_scc1 .Lattn_h2_noload
	v_add_u32_e32 v200, 0x41, v248
	v_lshl_add_u64 v[2:3], v[200:201], 2, s[66:67]
	v_add_u32_e32 v200, 0x20000, v14
	v_lshlrev_b64 v[10:11], 1, v[200:201]
	v_add_u32_e32 v200, 0x30000, v14
	v_lshlrev_b64 v[12:13], 1, v[200:201]
	global_load_dword v246, v[2:3], off
	v_lshl_add_u64 v[2:3], s[64:65], 0, v[10:11]
	v_lshl_add_u64 v[6:7], s[64:65], 0, v[12:13]
	v_lshl_add_u64 v[10:11], s[62:63], 0, v[10:11]
	v_lshl_add_u64 v[176:177], s[62:63], 0, v[12:13]
	global_load_dwordx4 v[2:5], v[2:3], off
	s_nop 0
	global_load_dwordx4 v[6:9], v[6:7], off
	s_nop 0
	global_load_dwordx4 v[10:13], v[10:11], off
	s_nop 0
	global_load_dwordx4 v[176:179], v[176:177], off

; __device__ __forceinline__ void mask_tile(f32x16& p0, f32x16& p1, int dq, unsigned W) {
;     const float NEG = -__builtin_inff();
; #pragma unroll
;     for (int r = 0; r < 16; ++r) {
;         const int c = (r & 3) + 8 * (r >> 2);
;         if ((unsigned)(dq - c) >= W) p0[r] = NEG;
;         if ((unsigned)(dq - c - 32) >= W) p1[r] = NEG;
;     }
; }
.Lattn_h2_nowrite:
	v_mfma_f32_32x32x16_bf16 v[16:31], v[180:183], v[196:199], v[16:31]
	s_cmp_le_i32 s4, s57
	s_cselect_b64 s[4:5], -1, 0
	s_cmp_gt_i32 s69, s58
	s_cselect_b64 s[72:73], -1, 0
	s_and_b64 s[4:5], s[4:5], s[72:73]
	s_and_b64 vcc, exec, s[4:5]
	v_mfma_f32_32x32x16_bf16 v[16:31], v[184:187], v[202:205], v[16:31]
	v_mfma_f32_32x32x16_bf16 v[16:31], v[188:191], v[206:209], v[16:31]
	v_mfma_f32_32x32x16_bf16 v[16:31], v[192:195], v[210:213], v[16:31]
	s_waitcnt lgkmcnt(0)
	s_barrier
	s_cbranch_vccnz .LBB0_1257
	v_add_u32_e32 v0, 0x103b, v243
	v_cmp_gt_u32_e32 vcc, s81, v0
	v_add_u32_e32 v0, 27, v243
	s_nop 0
	v_cndmask_b32_e32 v128, v216, v128, vcc
	v_cmp_lt_u32_e32 vcc, s82, v0
	v_add_u32_e32 v0, 58, v243
	s_nop 0
	v_cndmask_b32_e32 v112, v216, v112, vcc
	v_cmp_lt_u32_e32 vcc, s82, v0
	v_add_u32_e32 v0, 26, v243
	s_nop 0
	v_cndmask_b32_e32 v129, v216, v129, vcc
	v_cmp_lt_u32_e32 vcc, s82, v0
	v_add_u32_e32 v0, 57, v243
	s_nop 0
	v_cndmask_b32_e32 v113, v216, v113, vcc
	v_cmp_lt_u32_e32 vcc, s82, v0
	v_add_u32_e32 v0, 25, v243
	s_nop 0
	v_cndmask_b32_e32 v130, v216, v130, vcc
	v_cmp_lt_u32_e32 vcc, s82, v0
	v_add_u32_e32 v0, 56, v243
	s_nop 0
	v_cndmask_b32_e32 v114, v216, v114, vcc
	v_cmp_lt_u32_e32 vcc, s82, v0
	v_add_u32_e32 v0, 24, v243
	s_nop 0
	v_cndmask_b32_e32 v131, v216, v131, vcc
	v_cmp_lt_u32_e32 vcc, s82, v0
	v_add_u32_e32 v0, 51, v243
	s_nop 0
	v_cndmask_b32_e32 v115, v216, v115, vcc
	v_cmp_lt_u32_e32 vcc, s82, v0
	v_add_u32_e32 v0, 19, v243
	s_nop 0
	v_cndmask_b32_e32 v132, v216, v132, vcc
	v_cmp_lt_u32_e32 vcc, s82, v0
	v_add_u32_e32 v0, 50, v243
	s_nop 0
	v_cndmask_b32_e32 v116, v216, v116, vcc
	v_cmp_lt_u32_e32 vcc, s82, v0
	v_add_u32_e32 v0, 18, v243
	s_nop 0
	v_cndmask_b32_e32 v133, v216, v133, vcc
	v_cmp_lt_u32_e32 vcc, s82, v0
	v_add_u32_e32 v0, 49, v243
	s_nop 0
	v_cndmask_b32_e32 v117, v216, v117, vcc
	v_cmp_lt_u32_e32 vcc, s82, v0
	v_add_u32_e32 v0, 17, v243
	s_nop 0
	v_cndmask_b32_e32 v134, v216, v134, vcc
	v_cmp_lt_u32_e32 vcc, s82, v0
	v_add_u32_e32 v0, 48, v243
	s_nop 0
	v_cndmask_b32_e32 v118, v216, v118, vcc
	v_cmp_lt_u32_e32 vcc, s82, v0
	v_add_u32_e32 v0, 16, v243
	s_nop 0
	v_cndmask_b32_e32 v135, v216, v135, vcc
	v_cmp_lt_u32_e32 vcc, s82, v0
	v_add_u32_e32 v0, 43, v243
	s_nop 0
	v_cndmask_b32_e32 v119, v216, v119, vcc
	v_cmp_lt_u32_e32 vcc, s82, v0
	v_add_u32_e32 v0, 11, v243
	s_nop 0
	v_cndmask_b32_e32 v136, v216, v136, vcc
	v_cmp_lt_u32_e32 vcc, s82, v0
	v_add_u32_e32 v0, 42, v243
	s_nop 0
	v_cndmask_b32_e32 v120, v216, v120, vcc
	v_cmp_lt_u32_e32 vcc, s82, v0
	v_add_u32_e32 v0, 10, v243
	s_nop 0
	v_cndmask_b32_e32 v137, v216, v137, vcc
	v_cmp_lt_u32_e32 vcc, s82, v0
	v_add_u32_e32 v0, 41, v243
	s_nop 0
	v_cndmask_b32_e32 v121, v216, v121, vcc
	v_cmp_lt_u32_e32 vcc, s82, v0
	v_add_u32_e32 v0, 9, v243
	s_nop 0
	v_cndmask_b32_e32 v138, v216, v138, vcc
	v_cmp_lt_u32_e32 vcc, s82, v0
	v_add_u32_e32 v0, 40, v243
	s_nop 0
	v_cndmask_b32_e32 v122, v216, v122, vcc
	v_cmp_lt_u32_e32 vcc, s82, v0
	v_add_u32_e32 v0, 8, v243
	s_nop 0
	v_cndmask_b32_e32 v139, v216, v139, vcc
	v_cmp_lt_u32_e32 vcc, s82, v0
	v_add_u32_e32 v0, 35, v243
	s_nop 0
	v_cndmask_b32_e32 v123, v216, v123, vcc
	v_cmp_lt_u32_e32 vcc, s82, v0
	v_add_u32_e32 v0, 3, v243
	s_nop 0
	v_cndmask_b32_e32 v140, v216, v140, vcc
	v_cmp_lt_u32_e32 vcc, s82, v0
	v_add_u32_e32 v0, 34, v243
	s_nop 0
	v_cndmask_b32_e32 v124, v216, v124, vcc
	v_cmp_lt_u32_e32 vcc, s82, v0
	v_add_u32_e32 v0, 2, v243
	s_nop 0
	v_cndmask_b32_e32 v141, v216, v141, vcc
	v_cmp_lt_u32_e32 vcc, s82, v0
	v_add_u32_e32 v0, 33, v243
	s_nop 0
	v_cndmask_b32_e32 v125, v216, v125, vcc
	v_cmp_lt_u32_e32 vcc, s82, v0
	v_add_u32_e32 v0, 1, v243
	s_nop 0
	v_cndmask_b32_e32 v142, v216, v142, vcc
	v_cmp_lt_u32_e32 vcc, s82, v0
	v_add_u32_e32 v0, 32, v243
	s_nop 0
	v_cndmask_b32_e32 v126, v216, v126, vcc
	v_cmp_lt_u32_e32 vcc, s82, v0
	s_nop 1
	v_cndmask_b32_e32 v143, v216, v143, vcc
	v_cmp_lt_u32_e32 vcc, s82, v243
	s_nop 1
	v_cndmask_b32_e32 v127, v216, v127, vcc
